# v32 + nt (non-temporal) cache hint on prep_rows' 8 streaming f32 input loads, so the one-pass 335 MB stream does not evict the bf16 output reused by the next phase; 4th variant since v30, prior three
# speedup vs baseline: 1.0046x; 1.0046x over previous
; DI int tid_opaque() { int t = threadIdx.x; asm volatile("" : "+v"(t)); return t; }
; DI void prep_rows(const Params& p) {
;   const int tt_ = tid_opaque();
;   const int l = tt_ & 63, gw = blockIdx.x * 8 + (tt_ >> 6), nw = gridDim.x * 8;
;   for (int row = gw; row < T_TOK; row += nw) {
;     const float* src = row < TP ? p.x_prompt + (long)row * 1024 : p.x_sample + (long)(row - TP) * 1024;
;     float4 v[4];
;     float s = 0.f;
; #pragma unroll
;     for (int i = 0; i < 4; ++i) {
;       v[i] = ((const float4*)src)[l + 64 * i];
.Lprio_done:
	v_and_b32_e32 v182, 0x3ff, v0
	s_add_u32 s96, s0, 0x8a8
	v_mov_b32_e32 v1, v182
	s_addc_u32 s97, s1, 0
	s_lshl_b32 s92, s2, 3
	v_ashrrev_i32_e32 v2, 6, v1
	v_add_u32_e32 v2, s92, v2
	s_mov_b32 s3, 0x14000
	s_mov_b32 s82, s2
	s_waitcnt lgkmcnt(0)
	s_lshl_b32 s34, s42, 3
	v_cmp_gt_i32_e32 vcc, s3, v2
	v_mbcnt_lo_u32_b32 v183, -1, 0
	s_and_saveexec_b64 s[8:9], vcc
	s_cbranch_execz .LBB0_7
	v_mbcnt_hi_u32_b32 v3, -1, v183
	v_and_b32_e32 v10, 63, v1
	v_and_b32_e32 v1, 64, v3
	v_add_u32_e32 v4, 64, v1
	v_xor_b32_e32 v1, 1, v3
	v_cmp_lt_i32_e64 s[4:5], v1, v4
	v_xor_b32_e32 v6, 2, v3
	s_load_dwordx2 s[10:11], s[0:1], 0x60
	v_cndmask_b32_e64 v1, v3, v1, s[4:5]
	v_cmp_lt_i32_e64 s[4:5], v6, v4
	v_mov_b32_e32 v5, 0
	s_ashr_i32 s35, s34, 31
	v_cndmask_b32_e64 v6, v3, v6, s[4:5]
	v_lshlrev_b32_e32 v16, 2, v6
	v_xor_b32_e32 v6, 4, v3
	v_cmp_lt_i32_e64 s[4:5], v6, v4
	v_cmp_eq_u32_e32 vcc, 0, v10
	v_lshlrev_b32_e32 v1, 2, v1
	v_cndmask_b32_e64 v6, v3, v6, s[4:5]
	v_lshlrev_b32_e32 v17, 2, v6
	v_xor_b32_e32 v6, 8, v3
	v_cmp_lt_i32_e64 s[4:5], v6, v4
	s_lshl_b64 s[12:13], s[34:35], 12
	s_mov_b64 s[14:15], 0
	v_cndmask_b32_e64 v6, v3, v6, s[4:5]
	v_lshlrev_b32_e32 v18, 2, v6
	v_xor_b32_e32 v6, 16, v3
	v_cmp_lt_i32_e64 s[4:5], v6, v4
	s_movk_i32 s3, 0x3fff
	v_mov_b32_e32 v11, v5
	v_cndmask_b32_e64 v6, v3, v6, s[4:5]
	v_lshlrev_b32_e32 v19, 2, v6
	v_xor_b32_e32 v6, 32, v3
	v_cmp_lt_i32_e64 s[4:5], v6, v4
	v_lshlrev_b32_e32 v4, 3, v10
	v_lshlrev_b32_e32 v10, 4, v10
	v_cndmask_b32_e64 v3, v3, v6, s[4:5]
	s_load_dwordx4 s[4:7], s[0:1], 0x0
	s_waitcnt lgkmcnt(0)
	v_lshl_add_u64 v[6:7], s[10:11], 0, v[4:5]
	s_load_dwordx2 s[10:11], s[0:1], 0xf8
	v_lshlrev_b32_e32 v20, 2, v3
	v_ashrrev_i32_e32 v3, 31, v2
	v_lshlrev_b64 v[8:9], 12, v[2:3]
	v_lshl_add_u64 v[8:9], s[4:5], 0, v[8:9]
	s_mov_b32 s18, 0x13fff
	v_add_u32_e32 v72, 0xffffc000, v2
	v_mov_b32_e32 v73, 0
	v_cmp_lt_i32_e64 s[4:5], s3, v2
	v_lshlrev_b64 v[72:73], 12, v[72:73]
	s_waitcnt lgkmcnt(0)
	v_lshl_add_u64 v[72:73], s[6:7], 0, v[72:73]
	v_cndmask_b32_e64 v70, v8, v72, s[4:5]
	v_cndmask_b32_e64 v71, v9, v73, s[4:5]
	v_lshl_add_u64 v[70:71], v[70:71], 0, v[10:11]
	global_load_dwordx4 v[52:55], v[70:71], off nt
	global_load_dwordx4 v[56:59], v[70:71], off offset:1024 nt
	global_load_dwordx4 v[60:63], v[70:71], off offset:2048 nt
	global_load_dwordx4 v[64:67], v[70:71], off offset:3072 nt
	s_waitcnt vmcnt(0)
	s_branch .LBB0_3

; DI u32x2 pack4(float a, float b, float c, float d) { u32x2 r; r.x = pack2(a, b); r.y = pack2(c, d); return r; }
; DI void prep_rows(const Params& p) {
;     ...
;   for (int row = gw; row < T_TOK; row += nw) {
;     const float* src = row < TP ? p.x_prompt + (long)row * 1024 : p.x_sample + (long)(row - TP) * 1024;
;     float4 v[4];
;     float s = 0.f;
; #pragma unroll
;     for (int i = 0; i < 4; ++i) {
;       v[i] = ((const float4*)src)[l + 64 * i];
;       s += v[i].x * v[i].x + v[i].y * v[i].y + v[i].z * v[i].z + v[i].w * v[i].w;
;     }
; #pragma unroll
;     for (int o = 1; o < 64; o <<= 1) s += __shfl_xor(s, o);
; #pragma unroll
;     for (int i = 0; i < 4; ++i) {
;       *(u32x2*)(p.buf0 + (long)row * 1024 + (l + 64 * i) * 4) = pack4(v[i].x, v[i].y, v[i].z, v[i].w);
;     }
;     if (l == 0) p.ssq[row] = s;
;   }
.LBB0_3:
	v_mov_b64_e32 v[12:13], v[2:3]
	v_lshl_add_u64 v[68:69], v[2:3], 0, s[34:35]
	v_lshl_add_u64 v[70:71], v[8:9], 0, s[12:13]
	v_mov_b32_e32 v73, 0
	v_add_u32_e32 v72, 0xffffc000, v68
	v_cmp_lt_i32_e64 s[4:5], s3, v68
	v_lshlrev_b64 v[72:73], 12, v[72:73]
	v_cmp_ge_i32_e64 s[16:17], s18, v68
	v_lshl_add_u64 v[72:73], s[6:7], 0, v[72:73]
	s_waitcnt vmcnt(4) lgkmcnt(0)
	v_mov_b64_e32 v[22:23], v[52:53]
	v_mov_b64_e32 v[24:25], v[54:55]
	v_mov_b64_e32 v[26:27], v[56:57]
	v_mov_b64_e32 v[28:29], v[58:59]
	v_mov_b64_e32 v[30:31], v[60:61]
	v_mov_b64_e32 v[32:33], v[62:63]
	v_mov_b64_e32 v[34:35], v[64:65]
	v_mov_b64_e32 v[36:37], v[66:67]
	v_cndmask_b32_e64 v70, v70, v72, s[4:5]
	v_cndmask_b32_e64 v71, v71, v73, s[4:5]
	v_lshl_add_u64 v[70:71], v[70:71], 0, v[10:11]
	s_and_saveexec_b64 s[4:5], s[16:17]
	global_load_dwordx4 v[52:55], v[70:71], off nt
	global_load_dwordx4 v[56:59], v[70:71], off offset:1024 nt
	global_load_dwordx4 v[60:63], v[70:71], off offset:2048 nt
	global_load_dwordx4 v[64:67], v[70:71], off offset:3072 nt
	s_or_b64 exec, exec, s[4:5]
	v_pk_mul_f32 v[14:15], v[22:23], v[22:23]
	v_pk_mul_f32 v[40:41], v[26:27], v[26:27]
	v_pk_mul_f32 v[38:39], v[24:25], v[24:25]
	v_pk_mul_f32 v[42:43], v[28:29], v[28:29]
	v_pk_mul_f32 v[44:45], v[30:31], v[30:31]
	v_add_f32_e32 v4, v40, v41
	v_add_f32_e32 v14, v14, v15
	v_pk_mul_f32 v[46:47], v[32:33], v[32:33]
	v_pk_mul_f32 v[48:49], v[34:35], v[34:35]
	v_add_f32_e32 v15, v44, v45
	v_add_f32_e32 v4, v4, v42
	v_add_f32_e32 v14, v14, v38
	v_pk_mul_f32 v[50:51], v[36:37], v[36:37]
	v_add_f32_e32 v21, v48, v49
	v_add_f32_e32 v15, v15, v46
	v_add_f32_e32 v4, v4, v43
	v_add_f32_e32 v14, v14, v39
	v_add_f32_e32 v21, v21, v50
	v_add_f32_e32 v15, v15, v47
	v_add_f32_e32 v4, v14, v4
	v_add_f32_e32 v21, v21, v51
	v_add_f32_e32 v4, v4, v15
	v_add_f32_e32 v4, v4, v21
	ds_bpermute_b32 v14, v1, v4
	s_waitcnt lgkmcnt(0)
	v_add_f32_e32 v4, v4, v14
	ds_bpermute_b32 v14, v16, v4
	s_waitcnt lgkmcnt(0)
	v_add_f32_e32 v4, v4, v14
	ds_bpermute_b32 v21, v17, v4
	v_lshlrev_b64 v[14:15], 11, v[12:13]
	v_lshl_add_u64 v[38:39], v[6:7], 0, v[14:15]
	v_cvt_pk_bf16_f32 v14, v22, v23
	v_cvt_pk_bf16_f32 v15, v24, v25
	s_waitcnt lgkmcnt(0)
	v_add_f32_e32 v4, v4, v21
	ds_bpermute_b32 v21, v18, v4
	v_cvt_pk_bf16_f32 v22, v26, v27
	v_cvt_pk_bf16_f32 v23, v28, v29
	global_store_dwordx2 v[38:39], v[14:15], off
	global_store_dwordx2 v[38:39], v[22:23], off offset:512
	v_cvt_pk_bf16_f32 v24, v30, v31
	s_waitcnt lgkmcnt(0)
	v_add_f32_e32 v4, v4, v21
	ds_bpermute_b32 v21, v19, v4
	v_cvt_pk_bf16_f32 v25, v32, v33
	v_cvt_pk_bf16_f32 v22, v34, v35
	v_cvt_pk_bf16_f32 v23, v36, v37
	global_store_dwordx2 v[38:39], v[24:25], off offset:1024
	s_waitcnt lgkmcnt(0)
	v_add_f32_e32 v4, v4, v21
	ds_bpermute_b32 v14, v20, v4
	global_store_dwordx2 v[38:39], v[22:23], off offset:1536
	s_and_saveexec_b64 s[4:5], vcc
	s_cbranch_execz .LBB0_2
	s_waitcnt lgkmcnt(0)
	v_add_f32_e32 v4, v4, v14
	v_lshl_add_u64 v[12:13], v[12:13], 2, s[10:11]
	global_store_dword v[12:13], v4, off
	s_branch .LBB0_2
